# GEMM K-loop: redundant mid-burst s_setprio 0/1 pairs removed (priority stays raised through each 32-MFMA burst)
# baseline (speedup 1.0000x reference)
.LBB0_173:
	s_add_i32 s92, s90, 2
	s_add_u32 s93, s16, 0x80
	s_addc_u32 s91, s17, 0
	s_add_i32 s8, 0, 0x10000
	s_cmp_eq_u32 s35, s90
	s_cselect_b32 s91, s47, s91
	s_cselect_b32 s90, s46, s93
	s_cselect_b32 vcc_hi, s87, s89
	s_cselect_b32 vcc_lo, s86, s14
	s_add_i32 s9, 0, 0x14000
	v_add_u32_e32 v142, s8, v195
	v_add_u32_e32 v172, s9, v195
	s_waitcnt lgkmcnt(0)
	ds_read_b128 v[130:133], v142
	ds_read_b128 v[134:137], v142 offset:1024
	ds_read_b128 v[138:141], v142 offset:2048
	ds_read_b128 v[142:145], v142 offset:3072
	ds_read_b128 v[146:149], v172
	ds_read_b128 v[150:153], v172 offset:1024
	ds_read_b128 v[154:157], v172 offset:2048
	ds_read_b128 v[172:175], v172 offset:3072
	v_lshl_add_u64 v[236:237], s[16:17], 0, v[168:169]
	s_add_i32 m0, s97, 0xc000
	ds_read_b128 v[176:179], v208
	ds_read_b128 v[180:183], v208 offset:1024
	ds_read_b128 v[212:215], v208 offset:2048
	ds_read_b128 v[216:219], v208 offset:3072
	ds_read_b128 v[220:223], v208 offset:4096
	ds_read_b128 v[224:227], v208 offset:5120
	ds_read_b128 v[228:231], v208 offset:6144
	ds_read_b128 v[232:235], v208 offset:7168
	global_load_lds_dwordx4 v[236:237], off
	v_lshl_add_u64 v[236:237], s[16:17], 0, v[170:171]
	s_add_i32 m0, s97, 0xe000
	s_nop 0
	global_load_lds_dwordx4 v[236:237], off
	s_waitcnt vmcnt(8)
	s_waitcnt lgkmcnt(0)
	s_barrier
	s_setprio 1
	s_waitcnt lgkmcnt(0)
	v_mfma_f32_16x16x32_bf16 v[126:129], v[130:133], v[176:179], v[126:129]
	v_mfma_f32_16x16x32_bf16 v[122:125], v[138:141], v[176:179], v[122:125]
	v_mfma_f32_16x16x32_bf16 v[114:117], v[130:133], v[212:215], v[114:117]
	v_mfma_f32_16x16x32_bf16 v[106:109], v[138:141], v[212:215], v[106:109]
	v_mfma_f32_16x16x32_bf16 v[98:101], v[130:133], v[220:223], v[98:101]
	v_mfma_f32_16x16x32_bf16 v[90:93], v[138:141], v[220:223], v[90:93]
	v_mfma_f32_16x16x32_bf16 v[82:85], v[130:133], v[228:231], v[82:85]
	v_mfma_f32_16x16x32_bf16 v[74:77], v[138:141], v[228:231], v[74:77]
	v_mfma_f32_16x16x32_bf16 v[126:129], v[134:137], v[180:183], v[126:129]
	v_mfma_f32_16x16x32_bf16 v[122:125], v[142:145], v[180:183], v[122:125]
	v_mfma_f32_16x16x32_bf16 v[114:117], v[134:137], v[216:219], v[114:117]
	v_mfma_f32_16x16x32_bf16 v[106:109], v[142:145], v[216:219], v[106:109]
	v_mfma_f32_16x16x32_bf16 v[98:101], v[134:137], v[224:227], v[98:101]
	v_mfma_f32_16x16x32_bf16 v[90:93], v[142:145], v[224:227], v[90:93]
	v_mfma_f32_16x16x32_bf16 v[82:85], v[134:137], v[232:235], v[82:85]
	v_mfma_f32_16x16x32_bf16 v[74:77], v[142:145], v[232:235], v[74:77]
	v_mfma_f32_16x16x32_bf16 v[118:121], v[146:149], v[176:179], v[118:121]
	v_mfma_f32_16x16x32_bf16 v[110:113], v[154:157], v[176:179], v[110:113]
	v_mfma_f32_16x16x32_bf16 v[102:105], v[146:149], v[212:215], v[102:105]
	v_mfma_f32_16x16x32_bf16 v[94:97], v[154:157], v[212:215], v[94:97]
	v_mfma_f32_16x16x32_bf16 v[86:89], v[146:149], v[220:223], v[86:89]
	v_mfma_f32_16x16x32_bf16 v[78:81], v[154:157], v[220:223], v[78:81]
	v_mfma_f32_16x16x32_bf16 v[70:73], v[146:149], v[228:231], v[70:73]
	v_mfma_f32_16x16x32_bf16 v[66:69], v[154:157], v[228:231], v[66:69]
	v_mfma_f32_16x16x32_bf16 v[118:121], v[150:153], v[180:183], v[118:121]
	v_mfma_f32_16x16x32_bf16 v[110:113], v[172:175], v[180:183], v[110:113]
	v_mfma_f32_16x16x32_bf16 v[102:105], v[150:153], v[216:219], v[102:105]
	v_mfma_f32_16x16x32_bf16 v[94:97], v[172:175], v[216:219], v[94:97]
	v_mfma_f32_16x16x32_bf16 v[86:89], v[150:153], v[224:227], v[86:89]
	v_mfma_f32_16x16x32_bf16 v[78:81], v[172:175], v[224:227], v[78:81]
	v_mfma_f32_16x16x32_bf16 v[70:73], v[150:153], v[232:235], v[70:73]
	v_mfma_f32_16x16x32_bf16 v[66:69], v[172:175], v[232:235], v[66:69]
	s_setprio 0
	s_barrier
	s_add_i32 s8, s8, s96
	v_lshl_add_u64 v[236:237], vcc, 0, v[0:1]
	s_mov_b32 m0, s8
	ds_read_b128 v[176:179], v208 offset:16384
	ds_read_b128 v[180:183], v208 offset:17408
	ds_read_b128 v[212:215], v208 offset:18432
	ds_read_b128 v[216:219], v208 offset:19456
	ds_read_b128 v[220:223], v208 offset:20480
	ds_read_b128 v[224:227], v208 offset:21504
	ds_read_b128 v[228:231], v208 offset:22528
	ds_read_b128 v[232:235], v208 offset:23552
	global_load_lds_dwordx4 v[236:237], off
	s_add_i32 m0, s8, 0x2000
	v_lshl_add_u64 v[238:239], vcc, 0, v[162:163]
	s_add_u32 vcc_lo, vcc_lo, s74
	s_addc_u32 vcc_hi, vcc_hi, s75
	s_add_i32 s8, s9, s96
	global_load_lds_dwordx4 v[238:239], off
	v_lshl_add_u64 v[240:241], vcc, 0, v[0:1]
	s_mov_b32 m0, s8
	v_lshl_add_u64 v[242:243], vcc, 0, v[162:163]
	global_load_lds_dwordx4 v[240:241], off
	s_add_i32 m0, s8, 0x2000
	v_lshl_add_u64 v[244:245], s[90:91], 0, v[158:159]
	global_load_lds_dwordx4 v[242:243], off
	s_mov_b32 m0, s97
	v_lshl_add_u64 v[246:247], s[90:91], 0, v[160:161]
	global_load_lds_dwordx4 v[244:245], off
	s_mov_b32 m0, s98
	s_nop 0
	global_load_lds_dwordx4 v[246:247], off
	s_waitcnt vmcnt(8)
	s_waitcnt lgkmcnt(0)
	s_barrier
	s_setprio 1
	s_waitcnt lgkmcnt(0)
	v_mfma_f32_16x16x32_bf16 v[62:65], v[130:133], v[176:179], v[62:65]
	v_mfma_f32_16x16x32_bf16 v[58:61], v[138:141], v[176:179], v[58:61]
	v_mfma_f32_16x16x32_bf16 v[50:53], v[130:133], v[212:215], v[50:53]
	v_mfma_f32_16x16x32_bf16 v[42:45], v[138:141], v[212:215], v[42:45]
	v_mfma_f32_16x16x32_bf16 v[34:37], v[130:133], v[220:223], v[34:37]
	v_mfma_f32_16x16x32_bf16 v[26:29], v[138:141], v[220:223], v[26:29]
	v_mfma_f32_16x16x32_bf16 v[18:21], v[130:133], v[228:231], v[18:21]
	v_mfma_f32_16x16x32_bf16 v[10:13], v[138:141], v[228:231], v[10:13]
	v_mfma_f32_16x16x32_bf16 v[62:65], v[134:137], v[180:183], v[62:65]
	v_mfma_f32_16x16x32_bf16 v[58:61], v[142:145], v[180:183], v[58:61]
	v_mfma_f32_16x16x32_bf16 v[50:53], v[134:137], v[216:219], v[50:53]
	v_mfma_f32_16x16x32_bf16 v[42:45], v[142:145], v[216:219], v[42:45]
	v_mfma_f32_16x16x32_bf16 v[34:37], v[134:137], v[224:227], v[34:37]
	v_mfma_f32_16x16x32_bf16 v[26:29], v[142:145], v[224:227], v[26:29]
	v_mfma_f32_16x16x32_bf16 v[18:21], v[134:137], v[232:235], v[18:21]
	v_mfma_f32_16x16x32_bf16 v[10:13], v[142:145], v[232:235], v[10:13]
	v_mfma_f32_16x16x32_bf16 v[54:57], v[146:149], v[176:179], v[54:57]
	v_mfma_f32_16x16x32_bf16 v[46:49], v[154:157], v[176:179], v[46:49]
	v_mfma_f32_16x16x32_bf16 v[38:41], v[146:149], v[212:215], v[38:41]
	v_mfma_f32_16x16x32_bf16 v[30:33], v[154:157], v[212:215], v[30:33]
	v_mfma_f32_16x16x32_bf16 v[22:25], v[146:149], v[220:223], v[22:25]
	v_mfma_f32_16x16x32_bf16 v[14:17], v[154:157], v[220:223], v[14:17]
	v_mfma_f32_16x16x32_bf16 v[6:9], v[146:149], v[228:231], v[6:9]
	v_mfma_f32_16x16x32_bf16 v[2:5], v[154:157], v[228:231], v[2:5]
	v_mfma_f32_16x16x32_bf16 v[54:57], v[150:153], v[180:183], v[54:57]
	v_mfma_f32_16x16x32_bf16 v[46:49], v[172:175], v[180:183], v[46:49]
	v_mfma_f32_16x16x32_bf16 v[38:41], v[150:153], v[216:219], v[38:41]
	v_mfma_f32_16x16x32_bf16 v[30:33], v[172:175], v[216:219], v[30:33]
	v_mfma_f32_16x16x32_bf16 v[22:25], v[150:153], v[224:227], v[22:25]
	v_mfma_f32_16x16x32_bf16 v[14:17], v[172:175], v[224:227], v[14:17]
	v_mfma_f32_16x16x32_bf16 v[6:9], v[150:153], v[232:235], v[6:9]
	v_mfma_f32_16x16x32_bf16 v[2:5], v[172:175], v[232:235], v[2:5]
	s_setprio 0
	s_barrier
	s_add_i32 s8, 0, 0x18000
	s_add_i32 s9, 0, 0x1c000
	v_add_u32_e32 v142, s8, v195
	v_add_u32_e32 v172, s9, v195
	ds_read_b128 v[130:133], v142
	ds_read_b128 v[134:137], v142 offset:1024
	ds_read_b128 v[138:141], v142 offset:2048
	ds_read_b128 v[142:145], v142 offset:3072
	ds_read_b128 v[146:149], v172
	ds_read_b128 v[150:153], v172 offset:1024
	ds_read_b128 v[154:157], v172 offset:2048
	ds_read_b128 v[172:175], v172 offset:3072
	s_add_u32 s90, s90, s72
	s_addc_u32 s91, s91, s73
	s_mov_b32 m0, s99
	v_lshl_add_u64 v[248:249], s[90:91], 0, v[158:159]
	ds_read_b128 v[176:179], v208 offset:32768
	ds_read_b128 v[180:183], v208 offset:33792
	ds_read_b128 v[212:215], v208 offset:34816
	ds_read_b128 v[216:219], v208 offset:35840
	ds_read_b128 v[220:223], v208 offset:36864
	ds_read_b128 v[224:227], v208 offset:37888
	ds_read_b128 v[228:231], v208 offset:38912
	ds_read_b128 v[232:235], v208 offset:39936
	global_load_lds_dwordx4 v[248:249], off
	v_lshl_add_u64 v[248:249], s[90:91], 0, v[160:161]
	s_mov_b32 m0, s48
	s_nop 0
	global_load_lds_dwordx4 v[248:249], off
	s_waitcnt vmcnt(8)
	s_waitcnt lgkmcnt(0)
	s_barrier
	s_setprio 1
	s_waitcnt lgkmcnt(0)
	v_mfma_f32_16x16x32_bf16 v[126:129], v[130:133], v[176:179], v[126:129]
	v_mfma_f32_16x16x32_bf16 v[122:125], v[138:141], v[176:179], v[122:125]
	v_mfma_f32_16x16x32_bf16 v[114:117], v[130:133], v[212:215], v[114:117]
	v_mfma_f32_16x16x32_bf16 v[106:109], v[138:141], v[212:215], v[106:109]
	v_mfma_f32_16x16x32_bf16 v[98:101], v[130:133], v[220:223], v[98:101]
	v_mfma_f32_16x16x32_bf16 v[90:93], v[138:141], v[220:223], v[90:93]
	v_mfma_f32_16x16x32_bf16 v[82:85], v[130:133], v[228:231], v[82:85]
	v_mfma_f32_16x16x32_bf16 v[74:77], v[138:141], v[228:231], v[74:77]
	v_mfma_f32_16x16x32_bf16 v[126:129], v[134:137], v[180:183], v[126:129]
	v_mfma_f32_16x16x32_bf16 v[122:125], v[142:145], v[180:183], v[122:125]
	v_mfma_f32_16x16x32_bf16 v[114:117], v[134:137], v[216:219], v[114:117]
	v_mfma_f32_16x16x32_bf16 v[106:109], v[142:145], v[216:219], v[106:109]
	v_mfma_f32_16x16x32_bf16 v[98:101], v[134:137], v[224:227], v[98:101]
	v_mfma_f32_16x16x32_bf16 v[90:93], v[142:145], v[224:227], v[90:93]
	v_mfma_f32_16x16x32_bf16 v[82:85], v[134:137], v[232:235], v[82:85]
	v_mfma_f32_16x16x32_bf16 v[74:77], v[142:145], v[232:235], v[74:77]
	v_mfma_f32_16x16x32_bf16 v[118:121], v[146:149], v[176:179], v[118:121]
	v_mfma_f32_16x16x32_bf16 v[110:113], v[154:157], v[176:179], v[110:113]
	v_mfma_f32_16x16x32_bf16 v[102:105], v[146:149], v[212:215], v[102:105]
	v_mfma_f32_16x16x32_bf16 v[94:97], v[154:157], v[212:215], v[94:97]
	v_mfma_f32_16x16x32_bf16 v[86:89], v[146:149], v[220:223], v[86:89]
	v_mfma_f32_16x16x32_bf16 v[78:81], v[154:157], v[220:223], v[78:81]
	v_mfma_f32_16x16x32_bf16 v[70:73], v[146:149], v[228:231], v[70:73]
	v_mfma_f32_16x16x32_bf16 v[66:69], v[154:157], v[228:231], v[66:69]
	v_mfma_f32_16x16x32_bf16 v[118:121], v[150:153], v[180:183], v[118:121]
	v_mfma_f32_16x16x32_bf16 v[110:113], v[172:175], v[180:183], v[110:113]
	v_mfma_f32_16x16x32_bf16 v[102:105], v[150:153], v[216:219], v[102:105]
	v_mfma_f32_16x16x32_bf16 v[94:97], v[172:175], v[216:219], v[94:97]
	v_mfma_f32_16x16x32_bf16 v[86:89], v[150:153], v[224:227], v[86:89]
	v_mfma_f32_16x16x32_bf16 v[78:81], v[172:175], v[224:227], v[78:81]
	v_mfma_f32_16x16x32_bf16 v[70:73], v[150:153], v[232:235], v[70:73]
	v_mfma_f32_16x16x32_bf16 v[66:69], v[172:175], v[232:235], v[66:69]
	s_setprio 0
	s_barrier
	s_add_i32 s8, s8, s96
	v_lshl_add_u64 v[236:237], v[236:237], 0, s[18:19]
	s_mov_b32 m0, s8
	ds_read_b128 v[176:179], v208 offset:49152
	ds_read_b128 v[180:183], v208 offset:50176
	ds_read_b128 v[212:215], v208 offset:51200
	ds_read_b128 v[216:219], v208 offset:52224
	ds_read_b128 v[220:223], v208 offset:53248
	ds_read_b128 v[224:227], v208 offset:54272
	ds_read_b128 v[228:231], v208 offset:55296
	ds_read_b128 v[232:235], v208 offset:56320
	global_load_lds_dwordx4 v[236:237], off
	v_lshl_add_u64 v[236:237], v[238:239], 0, s[18:19]
	s_add_i32 m0, s8, 0x2000
	s_add_i32 s8, s9, s96
	global_load_lds_dwordx4 v[236:237], off
	v_lshl_add_u64 v[236:237], v[240:241], 0, s[18:19]
	s_mov_b32 m0, s8
	s_nop 0
	global_load_lds_dwordx4 v[236:237], off
	v_lshl_add_u64 v[236:237], v[242:243], 0, s[18:19]
	s_add_i32 m0, s8, 0x2000
	s_nop 0
	global_load_lds_dwordx4 v[236:237], off
	v_lshl_add_u64 v[236:237], v[244:245], 0, s[18:19]
	s_mov_b32 m0, s31
	s_nop 0
	global_load_lds_dwordx4 v[236:237], off
	v_lshl_add_u64 v[236:237], v[246:247], 0, s[18:19]
	s_mov_b32 m0, s34
	s_nop 0
	global_load_lds_dwordx4 v[236:237], off
	s_waitcnt vmcnt(8)
	s_waitcnt lgkmcnt(0)
	s_barrier
	s_setprio 1
	s_waitcnt lgkmcnt(0)
	v_mfma_f32_16x16x32_bf16 v[62:65], v[130:133], v[176:179], v[62:65]
	v_mfma_f32_16x16x32_bf16 v[58:61], v[138:141], v[176:179], v[58:61]
	v_mfma_f32_16x16x32_bf16 v[50:53], v[130:133], v[212:215], v[50:53]
	v_mfma_f32_16x16x32_bf16 v[42:45], v[138:141], v[212:215], v[42:45]
	v_mfma_f32_16x16x32_bf16 v[34:37], v[130:133], v[220:223], v[34:37]
	v_mfma_f32_16x16x32_bf16 v[26:29], v[138:141], v[220:223], v[26:29]
	v_mfma_f32_16x16x32_bf16 v[18:21], v[130:133], v[228:231], v[18:21]
	v_mfma_f32_16x16x32_bf16 v[10:13], v[138:141], v[228:231], v[10:13]
	v_mfma_f32_16x16x32_bf16 v[62:65], v[134:137], v[180:183], v[62:65]
	v_mfma_f32_16x16x32_bf16 v[58:61], v[142:145], v[180:183], v[58:61]
	v_mfma_f32_16x16x32_bf16 v[50:53], v[134:137], v[216:219], v[50:53]
	v_mfma_f32_16x16x32_bf16 v[42:45], v[142:145], v[216:219], v[42:45]
	v_mfma_f32_16x16x32_bf16 v[34:37], v[134:137], v[224:227], v[34:37]
	v_mfma_f32_16x16x32_bf16 v[26:29], v[142:145], v[224:227], v[26:29]
	v_mfma_f32_16x16x32_bf16 v[18:21], v[134:137], v[232:235], v[18:21]
	v_mfma_f32_16x16x32_bf16 v[10:13], v[142:145], v[232:235], v[10:13]
	v_mfma_f32_16x16x32_bf16 v[54:57], v[146:149], v[176:179], v[54:57]
	v_mfma_f32_16x16x32_bf16 v[46:49], v[154:157], v[176:179], v[46:49]
	v_mfma_f32_16x16x32_bf16 v[38:41], v[146:149], v[212:215], v[38:41]
	v_mfma_f32_16x16x32_bf16 v[30:33], v[154:157], v[212:215], v[30:33]
	v_mfma_f32_16x16x32_bf16 v[22:25], v[146:149], v[220:223], v[22:25]
	v_mfma_f32_16x16x32_bf16 v[14:17], v[154:157], v[220:223], v[14:17]
	v_mfma_f32_16x16x32_bf16 v[6:9], v[146:149], v[228:231], v[6:9]
	v_mfma_f32_16x16x32_bf16 v[2:5], v[154:157], v[228:231], v[2:5]
	v_mfma_f32_16x16x32_bf16 v[54:57], v[150:153], v[180:183], v[54:57]
	v_mfma_f32_16x16x32_bf16 v[46:49], v[172:175], v[180:183], v[46:49]
	v_mfma_f32_16x16x32_bf16 v[38:41], v[150:153], v[216:219], v[38:41]
	v_mfma_f32_16x16x32_bf16 v[30:33], v[172:175], v[216:219], v[30:33]
	v_mfma_f32_16x16x32_bf16 v[22:25], v[150:153], v[224:227], v[22:25]
	v_mfma_f32_16x16x32_bf16 v[14:17], v[172:175], v[224:227], v[14:17]
	v_mfma_f32_16x16x32_bf16 v[6:9], v[150:153], v[232:235], v[6:9]
	v_mfma_f32_16x16x32_bf16 v[2:5], v[172:175], v[232:235], v[2:5]
	s_setprio 0
	s_barrier
	s_add_u32 s16, s16, 0x100
	s_addc_u32 s17, s17, 0
	s_add_u32 s14, s14, 0x100
	s_addc_u32 s89, s89, 0
	s_cmp_ge_u32 s92, s30
	s_mov_b32 s90, s92
	s_cbranch_scc0 .LBB0_173
	s_and_b64 vcc, exec, s[82:83]
	s_cbranch_vccnz .LBB0_177
	s_andn2_b64 vcc, exec, s[78:79]
	s_mov_b64 s[16:17], -1
	s_cbranch_vccz .LBB0_178
